# SSD conv stages (chunk state and output units): rows warmed into cache with discarded loads ahead of the one-row-at-a-time load/compute chain; on top of the attention LDS prefetch
# speedup vs baseline: 1.0428x; 1.0079x over previous
; #define LAS __attribute__((address_space(3)))
; __device__ __forceinline__ unsigned pk2(float lo, float hi) { unsigned r; asm volatile("v_cvt_pk_bf16_f32 %0, %1, %2" : "=v"(r) : "v"(lo), "v"(hi)); return r; }
; template <class Put>
; __device__ __forceinline__ void conv_pair32(const bf16* Pseq  , int L, int p0, int xch, const float* cw, const float* cb, const Put& put) {
;     float w0[5], w1[5];
; #pragma unroll
;     for (int k = 0; k < 5; ++k) { w0[k] = cw[k * 1024 + xch]; w1[k] = cw[k * 1024 + xch + 1]; }
;     const float b0 = cb[xch], b1 = cb[xch + 1];
;     float a0 = 0.f, a1 = 0.f, a2 = 0.f, a3 = 0.f, a4 = 0.f, c0 = 0.f, c1 = 0.f, c2 = 0.f, c3 = 0.f, c4 = 0.f;
; #pragma unroll
;     for (int i = 0; i < 36; ++i) {
;         const int pos = p0 + i - 2;
;         unsigned raw = 0u;
;         if (pos >= 0 && pos < L) raw = *(const unsigned*)(Pseq + (size_t)pos * LDP + xch);
; __device__ __forceinline__ void ssd_state_unit(const Params& p, int layer, LAS unsigned char* lds, int b, int cc, int g) {
;     ...
;     for (int it = tid; it < 192 * 4; it += NT) {
;         const int pr = it % 192, q = it / 192, c0 = pr * 2;
;         const bool isx = c0 < 256;
;         const int xch = isx ? g * 256 + c0 : 512 + g * 128 + (c0 - 256);
;         LAS unsigned char* dst = isx ? lds + SS_XT + c0 * XT_PITCH : lds + SS_B + (c0 - 256) * BN_PITCH;
;         const int pitch = isx ? XT_PITCH : BN_PITCH;
;         conv_pair32(Pm + (size_t)G.Rseq0 * LDP + C_BX, G.L, G.pos0 + q * 32, xch, cw, cb, [&](int l, float v0, float v1) {
;             const unsigned pk = pk2(v0, v1); const int ll = q * 32 + l;
;             *(LAS unsigned short*)(dst + ll * 2) = (unsigned short)(pk & 0xffffu); *(LAS unsigned short*)(dst + pitch + ll * 2) = (unsigned short)(pk >> 16); });
.LBB0_460:
	s_mov_b32 s0, 0x2aaaaaab
	v_mul_hi_i32 v4, v2, s0
	v_lshrrev_b32_e32 v5, 31, v4
	v_ashrrev_i32_e32 v4, 5, v4
	v_add_u32_e32 v21, v4, v5
	s_movk_i32 s0, 0xff40
	v_mad_u64_u32 v[4:5], s[0:1], v21, s0, v[2:3]
	s_movk_i32 s0, 0x80
	s_nop 0
	v_cmp_gt_i32_e32 vcc, s0, v4
	s_movk_i32 s0, 0x7f
	v_cmp_lt_i32_e64 s[0:1], s0, v4
	s_and_saveexec_b64 s[18:19], s[0:1]
	s_xor_b64 s[0:1], exec, s[18:19]
	s_movk_i32 s18, 0xc0
	v_mul_lo_u32 v4, v21, s18
	v_sub_u32_e32 v4, v2, v4
	s_movk_i32 s18, 0x220
	v_mul_lo_u32 v4, v4, s18
	v_add_u32_e32 v4, s33, v4
	v_add_u32_e32 v18, 0xfffef000, v4
	s_or_saveexec_b64 s[0:1], s[0:1]
	v_mov_b32_e32 v23, 0x110
	s_xor_b64 exec, exec, s[0:1]
	s_mov_b32 s18, 0xfffe7400
	v_mad_u64_u32 v[18:19], s[18:19], v21, s18, v[0:1]
	v_mov_b32_e32 v23, 0x108
	s_or_b64 exec, exec, s[0:1]
	v_mov_b32_e32 v4, s16
	v_mov_b32_e32 v5, s17
	s_movk_i32 s0, 0x180
	v_cndmask_b32_e32 v4, v4, v5, vcc
	v_mul_lo_u32 v5, v21, s0
	v_sub_u32_e32 v4, v4, v5
	v_add_u32_e32 v16, v3, v4
	v_ashrrev_i32_e32 v17, 31, v16
	v_readlane_b32 s0, v254, 38
	v_lshlrev_b64 v[4:5], 2, v[16:17]
	v_readlane_b32 s1, v254, 39
	v_lshl_add_u32 v19, v21, 5, s3
	v_add_u32_e32 v24, -2, v19
	v_lshl_add_u64 v[10:11], s[0:1], 0, v[4:5]
	v_add_co_u32_e32 v12, vcc, 0x1000, v10
	s_movk_i32 s0, 0x3000
	s_nop 0
	v_addc_co_u32_e32 v13, vcc, 0, v11, vcc
	v_add_co_u32_e32 v8, vcc, s0, v10
	v_readlane_b32 s0, v254, 40
	s_nop 0
	v_addc_co_u32_e32 v9, vcc, 0, v11, vcc
	v_add_co_u32_e32 v14, vcc, 0x4000, v10
	v_readlane_b32 s1, v254, 41
	s_nop 0
	v_addc_co_u32_e32 v15, vcc, 0, v11, vcc
	global_load_dwordx2 v[6:7], v[8:9], off offset:-4096
	s_nop 0
	global_load_dwordx2 v[8:9], v[8:9], off
	s_nop 0
	global_load_dwordx2 v[10:11], v[10:11], off
	s_nop 0
	global_load_dwordx2 v[12:13], v[12:13], off
	s_nop 0
	global_load_dwordx2 v[14:15], v[14:15], off
	v_lshl_add_u64 v[4:5], s[0:1], 0, v[4:5]
	global_load_dwordx2 v[4:5], v[4:5], off
	v_cmp_lt_i32_e32 vcc, 1, v19
	v_cmp_gt_u32_e64 s[0:1], s14, v24
	v_lshl_add_u64 v[16:17], v[16:17], 1, s[6:7]
	v_add_u32_e32 v229, 2, v19
	v_add_u32_e32 v229, 1, v229
	v_mad_u64_u32 v[230:231], s[18:19], v229, s50, v[16:17]
	global_load_dword v228, v[230:231], off
	v_add_u32_e32 v229, 1, v229
	v_mad_u64_u32 v[230:231], s[18:19], v229, s50, v[16:17]
	global_load_dword v228, v[230:231], off
	v_add_u32_e32 v229, 1, v229
	v_mad_u64_u32 v[230:231], s[18:19], v229, s50, v[16:17]
	global_load_dword v228, v[230:231], off
	v_add_u32_e32 v229, 1, v229
	v_mad_u64_u32 v[230:231], s[18:19], v229, s50, v[16:17]
	global_load_dword v228, v[230:231], off
	v_add_u32_e32 v229, 1, v229
	v_mad_u64_u32 v[230:231], s[18:19], v229, s50, v[16:17]
	global_load_dword v228, v[230:231], off
	v_add_u32_e32 v229, 1, v229
	v_mad_u64_u32 v[230:231], s[18:19], v229, s50, v[16:17]
	global_load_dword v228, v[230:231], off
	v_add_u32_e32 v229, 1, v229
	v_mad_u64_u32 v[230:231], s[18:19], v229, s50, v[16:17]
	global_load_dword v228, v[230:231], off
	v_add_u32_e32 v229, 1, v229
	v_mad_u64_u32 v[230:231], s[18:19], v229, s50, v[16:17]
	global_load_dword v228, v[230:231], off
	v_add_u32_e32 v229, 1, v229
	v_mad_u64_u32 v[230:231], s[18:19], v229, s50, v[16:17]
	global_load_dword v228, v[230:231], off
	v_add_u32_e32 v229, 1, v229
	v_mad_u64_u32 v[230:231], s[18:19], v229, s50, v[16:17]
	global_load_dword v228, v[230:231], off
	v_add_u32_e32 v229, 1, v229
	v_mad_u64_u32 v[230:231], s[18:19], v229, s50, v[16:17]
	global_load_dword v228, v[230:231], off
	v_add_u32_e32 v229, 1, v229
	v_mad_u64_u32 v[230:231], s[18:19], v229, s50, v[16:17]
	global_load_dword v228, v[230:231], off
	v_add_u32_e32 v229, 1, v229
	v_mad_u64_u32 v[230:231], s[18:19], v229, s50, v[16:17]
	global_load_dword v228, v[230:231], off
	v_add_u32_e32 v229, 1, v229
	v_mad_u64_u32 v[230:231], s[18:19], v229, s50, v[16:17]
	global_load_dword v228, v[230:231], off
	v_add_u32_e32 v229, 1, v229
	v_mad_u64_u32 v[230:231], s[18:19], v229, s50, v[16:17]
	global_load_dword v228, v[230:231], off
	v_add_u32_e32 v229, 1, v229
	v_mad_u64_u32 v[230:231], s[18:19], v229, s50, v[16:17]
	global_load_dword v228, v[230:231], off
	v_add_u32_e32 v229, 1, v229
	v_mad_u64_u32 v[230:231], s[18:19], v229, s50, v[16:17]
	global_load_dword v228, v[230:231], off
	v_add_u32_e32 v229, 1, v229
	v_mad_u64_u32 v[230:231], s[18:19], v229, s50, v[16:17]
	global_load_dword v228, v[230:231], off
	v_add_u32_e32 v229, 1, v229
	v_mad_u64_u32 v[230:231], s[18:19], v229, s50, v[16:17]
	global_load_dword v228, v[230:231], off
	v_add_u32_e32 v229, 1, v229
	v_mad_u64_u32 v[230:231], s[18:19], v229, s50, v[16:17]
	global_load_dword v228, v[230:231], off
	v_add_u32_e32 v229, 1, v229
	v_mad_u64_u32 v[230:231], s[18:19], v229, s50, v[16:17]
	global_load_dword v228, v[230:231], off
	v_add_u32_e32 v229, 1, v229
	v_mad_u64_u32 v[230:231], s[18:19], v229, s50, v[16:17]
	global_load_dword v228, v[230:231], off
	v_add_u32_e32 v229, 1, v229
	v_mad_u64_u32 v[230:231], s[18:19], v229, s50, v[16:17]
	global_load_dword v228, v[230:231], off
	v_add_u32_e32 v229, 1, v229
	v_mad_u64_u32 v[230:231], s[18:19], v229, s50, v[16:17]
	global_load_dword v228, v[230:231], off
	v_add_u32_e32 v229, 1, v229
	v_mad_u64_u32 v[230:231], s[18:19], v229, s50, v[16:17]
	global_load_dword v228, v[230:231], off
	v_add_u32_e32 v229, 1, v229
	v_mad_u64_u32 v[230:231], s[18:19], v229, s50, v[16:17]
	global_load_dword v228, v[230:231], off
	v_add_u32_e32 v229, 1, v229
	v_mad_u64_u32 v[230:231], s[18:19], v229, s50, v[16:17]
	global_load_dword v228, v[230:231], off
	v_add_u32_e32 v229, 1, v229
	v_mad_u64_u32 v[230:231], s[18:19], v229, s50, v[16:17]
	global_load_dword v228, v[230:231], off
	v_add_u32_e32 v229, 1, v229
	v_mad_u64_u32 v[230:231], s[18:19], v229, s50, v[16:17]
	global_load_dword v228, v[230:231], off
	v_add_u32_e32 v229, 1, v229
	v_mad_u64_u32 v[230:231], s[18:19], v229, s50, v[16:17]
	global_load_dword v228, v[230:231], off
	v_add_u32_e32 v229, 1, v229
	v_mad_u64_u32 v[230:231], s[18:19], v229, s50, v[16:17]
	global_load_dword v228, v[230:231], off
	s_and_b64 s[18:19], vcc, s[0:1]
	v_mov_b32_e32 v27, 0
	v_mov_b32_e32 v22, 0
	s_and_saveexec_b64 s[0:1], s[18:19]
	s_cbranch_execz .LBB0_466
	v_mad_u64_u32 v[24:25], s[18:19], v24, s50, v[16:17]
	global_load_dword v22, v[24:25], off

; #define LAS __attribute__((address_space(3)))
; __device__ __forceinline__ unsigned pk2(float lo, float hi) { unsigned r; asm volatile("v_cvt_pk_bf16_f32 %0, %1, %2" : "=v"(r) : "v"(lo), "v"(hi)); return r; }
; template <class Put>
; __device__ __forceinline__ void conv_pair32(const bf16* Pseq  , int L, int p0, int xch, const float* cw, const float* cb, const Put& put) {
;     float w0[5], w1[5];
; #pragma unroll
;     for (int k = 0; k < 5; ++k) { w0[k] = cw[k * 1024 + xch]; w1[k] = cw[k * 1024 + xch + 1]; }
;     const float b0 = cb[xch], b1 = cb[xch + 1];
;     float a0 = 0.f, a1 = 0.f, a2 = 0.f, a3 = 0.f, a4 = 0.f, c0 = 0.f, c1 = 0.f, c2 = 0.f, c3 = 0.f, c4 = 0.f;
; #pragma unroll
;     for (int i = 0; i < 36; ++i) {
;         const int pos = p0 + i - 2;
;         unsigned raw = 0u;
;         if (pos >= 0 && pos < L) raw = *(const unsigned*)(Pseq + (size_t)pos * LDP + xch);
; __device__ __forceinline__ void ssd_out_unit(const Params& p, int layer, LAS unsigned char* lds, int b, int cc, int g, bool do_ssq = true) {
;     ...
;         } else {
;             const int n0 = (c0 - 256) & 127; const bool isC = (c0 - 256) >= 128;
;             LAS unsigned char* dst = lds + (isC ? SS_C : SS_B) + n0 * 2;
;             conv_pair32(Pm + (size_t)G.Rseq0 * LDP + C_BX, G.L, G.pos0 + q * 32, 512 + (isC ? 256 : 0) + g * 128 + n0, cw, cb, [&](int l, float v0, float v1) {
;                 *(LAS unsigned*)(dst + (q * 32 + l) * BN_PITCH) = pk2(v0, v1); });
.LBB0_791:
	v_ashrrev_i32_e32 v28, 8, v44
	v_and_b32_e32 v16, 0x1fe, v43
	s_movk_i32 s0, 0xff
	v_cmp_lt_u32_e32 vcc, s0, v16
	v_lshl_add_u32 v45, v28, 5, s19
	s_and_saveexec_b64 s[0:1], vcc
	s_xor_b64 s[12:13], exec, s[0:1]
	s_cbranch_execz .LBB0_865
	s_movk_i32 s0, 0x17f
	v_cmp_lt_u32_e64 s[0:1], s0, v16
	v_and_b32_e32 v12, 0x7e, v43
	v_readlane_b32 s4, v254, 38
	v_cndmask_b32_e64 v0, v217, v218, s[0:1]
	v_or3_b32 v13, v0, s21, v12
	v_lshlrev_b32_e32 v0, 2, v13
	v_readlane_b32 s5, v254, 39
	s_movk_i32 s2, 0x3000
	v_add_u32_e32 v14, -2, v45
	v_lshl_add_u64 v[4:5], s[4:5], 0, v[0:1]
	v_add_co_u32_e32 v6, vcc, 0x1000, v4
	s_nop 1
	v_addc_co_u32_e32 v7, vcc, 0, v5, vcc
	v_add_co_u32_e32 v8, vcc, s2, v4
	v_readlane_b32 s2, v254, 40
	s_nop 0
	v_addc_co_u32_e32 v9, vcc, 0, v5, vcc
	v_add_co_u32_e32 v10, vcc, 0x4000, v4
	v_readlane_b32 s3, v254, 41
	global_load_dwordx2 v[2:3], v[8:9], off offset:-4096
	global_load_dwordx2 v[20:21], v[8:9], off
	v_addc_co_u32_e32 v11, vcc, 0, v5, vcc
	global_load_dwordx2 v[4:5], v0, s[4:5]
	global_load_dwordx2 v[26:27], v[6:7], off
	global_load_dwordx2 v[8:9], v0, s[2:3]
	s_nop 0
	global_load_dwordx2 v[6:7], v[10:11], off
	v_lshlrev_b32_e32 v0, 1, v13
	v_cmp_lt_i32_e32 vcc, 1, v45
	v_cmp_gt_u32_e64 s[4:5], s20, v14
	v_lshl_add_u64 v[10:11], s[8:9], 0, v[0:1]
	v_add_u32_e32 v229, 2, v45
	v_add_u32_e32 v229, 1, v229
	v_mad_u64_u32 v[230:231], s[2:3], v229, s50, v[10:11]
	global_load_dword v228, v[230:231], off
	v_add_u32_e32 v229, 1, v229
	v_mad_u64_u32 v[230:231], s[2:3], v229, s50, v[10:11]
	global_load_dword v228, v[230:231], off
	v_add_u32_e32 v229, 1, v229
	v_mad_u64_u32 v[230:231], s[2:3], v229, s50, v[10:11]
	global_load_dword v228, v[230:231], off
	v_add_u32_e32 v229, 1, v229
	v_mad_u64_u32 v[230:231], s[2:3], v229, s50, v[10:11]
	global_load_dword v228, v[230:231], off
	v_add_u32_e32 v229, 1, v229
	v_mad_u64_u32 v[230:231], s[2:3], v229, s50, v[10:11]
	global_load_dword v228, v[230:231], off
	v_add_u32_e32 v229, 1, v229
	v_mad_u64_u32 v[230:231], s[2:3], v229, s50, v[10:11]
	global_load_dword v228, v[230:231], off
	v_add_u32_e32 v229, 1, v229
	v_mad_u64_u32 v[230:231], s[2:3], v229, s50, v[10:11]
	global_load_dword v228, v[230:231], off
	v_add_u32_e32 v229, 1, v229
	v_mad_u64_u32 v[230:231], s[2:3], v229, s50, v[10:11]
	global_load_dword v228, v[230:231], off
	v_add_u32_e32 v229, 1, v229
	v_mad_u64_u32 v[230:231], s[2:3], v229, s50, v[10:11]
	global_load_dword v228, v[230:231], off
	v_add_u32_e32 v229, 1, v229
	v_mad_u64_u32 v[230:231], s[2:3], v229, s50, v[10:11]
	global_load_dword v228, v[230:231], off
	v_add_u32_e32 v229, 1, v229
	v_mad_u64_u32 v[230:231], s[2:3], v229, s50, v[10:11]
	global_load_dword v228, v[230:231], off
	v_add_u32_e32 v229, 1, v229
	v_mad_u64_u32 v[230:231], s[2:3], v229, s50, v[10:11]
	global_load_dword v228, v[230:231], off
	v_add_u32_e32 v229, 1, v229
	v_mad_u64_u32 v[230:231], s[2:3], v229, s50, v[10:11]
	global_load_dword v228, v[230:231], off
	v_add_u32_e32 v229, 1, v229
	v_mad_u64_u32 v[230:231], s[2:3], v229, s50, v[10:11]
	global_load_dword v228, v[230:231], off
	v_add_u32_e32 v229, 1, v229
	v_mad_u64_u32 v[230:231], s[2:3], v229, s50, v[10:11]
	global_load_dword v228, v[230:231], off
	v_add_u32_e32 v229, 1, v229
	v_mad_u64_u32 v[230:231], s[2:3], v229, s50, v[10:11]
	global_load_dword v228, v[230:231], off
	v_add_u32_e32 v229, 1, v229
	v_mad_u64_u32 v[230:231], s[2:3], v229, s50, v[10:11]
	global_load_dword v228, v[230:231], off
	v_add_u32_e32 v229, 1, v229
	v_mad_u64_u32 v[230:231], s[2:3], v229, s50, v[10:11]
	global_load_dword v228, v[230:231], off
	v_add_u32_e32 v229, 1, v229
	v_mad_u64_u32 v[230:231], s[2:3], v229, s50, v[10:11]
	global_load_dword v228, v[230:231], off
	v_add_u32_e32 v229, 1, v229
	v_mad_u64_u32 v[230:231], s[2:3], v229, s50, v[10:11]
	global_load_dword v228, v[230:231], off
	v_add_u32_e32 v229, 1, v229
	v_mad_u64_u32 v[230:231], s[2:3], v229, s50, v[10:11]
	global_load_dword v228, v[230:231], off
	v_add_u32_e32 v229, 1, v229
	v_mad_u64_u32 v[230:231], s[2:3], v229, s50, v[10:11]
	global_load_dword v228, v[230:231], off
	v_add_u32_e32 v229, 1, v229
	v_mad_u64_u32 v[230:231], s[2:3], v229, s50, v[10:11]
	global_load_dword v228, v[230:231], off
	v_add_u32_e32 v229, 1, v229
	v_mad_u64_u32 v[230:231], s[2:3], v229, s50, v[10:11]
	global_load_dword v228, v[230:231], off
	v_add_u32_e32 v229, 1, v229
	v_mad_u64_u32 v[230:231], s[2:3], v229, s50, v[10:11]
	global_load_dword v228, v[230:231], off
	v_add_u32_e32 v229, 1, v229
	v_mad_u64_u32 v[230:231], s[2:3], v229, s50, v[10:11]
	global_load_dword v228, v[230:231], off
	v_add_u32_e32 v229, 1, v229
	v_mad_u64_u32 v[230:231], s[2:3], v229, s50, v[10:11]
	global_load_dword v228, v[230:231], off
	v_add_u32_e32 v229, 1, v229
	v_mad_u64_u32 v[230:231], s[2:3], v229, s50, v[10:11]
	global_load_dword v228, v[230:231], off
	v_add_u32_e32 v229, 1, v229
	v_mad_u64_u32 v[230:231], s[2:3], v229, s50, v[10:11]
	global_load_dword v228, v[230:231], off
	v_add_u32_e32 v229, 1, v229
	v_mad_u64_u32 v[230:231], s[2:3], v229, s50, v[10:11]
	global_load_dword v228, v[230:231], off
	v_add_u32_e32 v229, 1, v229
	v_mad_u64_u32 v[230:231], s[2:3], v229, s50, v[10:11]
	global_load_dword v228, v[230:231], off
	s_and_b64 s[4:5], vcc, s[4:5]
	v_mov_b32_e32 v13, 0
	v_mov_b32_e32 v0, 0
	s_and_saveexec_b64 s[2:3], s[4:5]
	s_cbranch_execz .LBB0_794
	v_mad_u64_u32 v[14:15], s[4:5], v14, s50, v[10:11]
	global_load_dword v0, v[14:15], off

; #define LAS __attribute__((address_space(3)))
; __device__ __forceinline__ unsigned pk2(float lo, float hi) { unsigned r; asm volatile("v_cvt_pk_bf16_f32 %0, %1, %2" : "=v"(r) : "v"(lo), "v"(hi)); return r; }
; template <class Put>
; __device__ __forceinline__ void conv_pair32(const bf16* Pseq  , int L, int p0, int xch, const float* cw, const float* cb, const Put& put) {
;     float w0[5], w1[5];
; #pragma unroll
;     for (int k = 0; k < 5; ++k) { w0[k] = cw[k * 1024 + xch]; w1[k] = cw[k * 1024 + xch + 1]; }
;     const float b0 = cb[xch], b1 = cb[xch + 1];
;     float a0 = 0.f, a1 = 0.f, a2 = 0.f, a3 = 0.f, a4 = 0.f, c0 = 0.f, c1 = 0.f, c2 = 0.f, c3 = 0.f, c4 = 0.f;
; #pragma unroll
;     for (int i = 0; i < 36; ++i) {
;         const int pos = p0 + i - 2;
;         unsigned raw = 0u;
;         if (pos >= 0 && pos < L) raw = *(const unsigned*)(Pseq + (size_t)pos * LDP + xch);
; __device__ __forceinline__ void ssd_out_unit(const Params& p, int layer, LAS unsigned char* lds, int b, int cc, int g, bool do_ssq = true) {
;     ...
;         if (c0 < 256) {
;             LAS unsigned char* dst = lds + SS_XT + c0 * XT_PITCH;
;             conv_pair32(Pm + (size_t)G.Rseq0 * LDP + C_BX, G.L, G.pos0 + q * 32, g * 256 + c0, cw, cb, [&](int l, float v0, float v1) {
;                 const unsigned pk = pk2(v0, v1); const int ll = q * 32 + l;
;                 *(LAS unsigned short*)(dst + ll * 2) = (unsigned short)(pk & 0xffffu); *(LAS unsigned short*)(dst + XT_PITCH + ll * 2) = (unsigned short)(pk >> 16); });
.LBB0_865:
	s_andn2_saveexec_b64 s[4:5], s[12:13]
	s_cbranch_execz .LBB0_790
	v_or_b32_e32 v14, s22, v16
	v_readlane_b32 s2, v254, 38
	v_lshlrev_b32_e32 v0, 2, v14
	v_readlane_b32 s3, v254, 39
	s_movk_i32 s0, 0x3000
	v_add_u32_e32 v17, -2, v45
	v_lshl_add_u64 v[2:3], s[2:3], 0, v[0:1]
	v_add_co_u32_e32 v4, vcc, 0x1000, v2
	v_mov_b32_e32 v18, 0
	s_nop 0
	v_addc_co_u32_e32 v5, vcc, 0, v3, vcc
	v_add_co_u32_e32 v6, vcc, 0x2000, v2
	s_nop 1
	v_addc_co_u32_e32 v7, vcc, 0, v3, vcc
	v_add_co_u32_e32 v8, vcc, s0, v2
	v_readlane_b32 s0, v254, 40
	s_nop 0
	v_addc_co_u32_e32 v9, vcc, 0, v3, vcc
	v_add_co_u32_e32 v2, vcc, 0x4000, v2
	v_readlane_b32 s1, v254, 41
	s_nop 0
	v_addc_co_u32_e32 v3, vcc, 0, v3, vcc
	global_load_dwordx2 v[4:5], v[4:5], off
	s_nop 0
	global_load_dwordx2 v[6:7], v[6:7], off
	s_nop 0
	global_load_dwordx2 v[8:9], v[8:9], off
	s_nop 0
	global_load_dwordx2 v[10:11], v[2:3], off
	global_load_dwordx2 v[12:13], v0, s[2:3]
	v_cmp_lt_i32_e32 vcc, 1, v45
	global_load_dwordx2 v[2:3], v0, s[0:1]
	v_lshlrev_b32_e32 v0, 1, v14
	v_cmp_gt_u32_e64 s[0:1], s20, v17
	v_lshl_add_u64 v[14:15], s[8:9], 0, v[0:1]
	v_add_u32_e32 v229, 2, v45
	v_add_u32_e32 v229, 1, v229
	v_mad_u64_u32 v[230:231], s[2:3], v229, s50, v[14:15]
	global_load_dword v228, v[230:231], off
	v_add_u32_e32 v229, 1, v229
	v_mad_u64_u32 v[230:231], s[2:3], v229, s50, v[14:15]
	global_load_dword v228, v[230:231], off
	v_add_u32_e32 v229, 1, v229
	v_mad_u64_u32 v[230:231], s[2:3], v229, s50, v[14:15]
	global_load_dword v228, v[230:231], off
	v_add_u32_e32 v229, 1, v229
	v_mad_u64_u32 v[230:231], s[2:3], v229, s50, v[14:15]
	global_load_dword v228, v[230:231], off
	v_add_u32_e32 v229, 1, v229
	v_mad_u64_u32 v[230:231], s[2:3], v229, s50, v[14:15]
	global_load_dword v228, v[230:231], off
	v_add_u32_e32 v229, 1, v229
	v_mad_u64_u32 v[230:231], s[2:3], v229, s50, v[14:15]
	global_load_dword v228, v[230:231], off
	v_add_u32_e32 v229, 1, v229
	v_mad_u64_u32 v[230:231], s[2:3], v229, s50, v[14:15]
	global_load_dword v228, v[230:231], off
	v_add_u32_e32 v229, 1, v229
	v_mad_u64_u32 v[230:231], s[2:3], v229, s50, v[14:15]
	global_load_dword v228, v[230:231], off
	v_add_u32_e32 v229, 1, v229
	v_mad_u64_u32 v[230:231], s[2:3], v229, s50, v[14:15]
	global_load_dword v228, v[230:231], off
	v_add_u32_e32 v229, 1, v229
	v_mad_u64_u32 v[230:231], s[2:3], v229, s50, v[14:15]
	global_load_dword v228, v[230:231], off
	v_add_u32_e32 v229, 1, v229
	v_mad_u64_u32 v[230:231], s[2:3], v229, s50, v[14:15]
	global_load_dword v228, v[230:231], off
	v_add_u32_e32 v229, 1, v229
	v_mad_u64_u32 v[230:231], s[2:3], v229, s50, v[14:15]
	global_load_dword v228, v[230:231], off
	v_add_u32_e32 v229, 1, v229
	v_mad_u64_u32 v[230:231], s[2:3], v229, s50, v[14:15]
	global_load_dword v228, v[230:231], off
	v_add_u32_e32 v229, 1, v229
	v_mad_u64_u32 v[230:231], s[2:3], v229, s50, v[14:15]
	global_load_dword v228, v[230:231], off
	v_add_u32_e32 v229, 1, v229
	v_mad_u64_u32 v[230:231], s[2:3], v229, s50, v[14:15]
	global_load_dword v228, v[230:231], off
	v_add_u32_e32 v229, 1, v229
	v_mad_u64_u32 v[230:231], s[2:3], v229, s50, v[14:15]
	global_load_dword v228, v[230:231], off
	v_add_u32_e32 v229, 1, v229
	v_mad_u64_u32 v[230:231], s[2:3], v229, s50, v[14:15]
	global_load_dword v228, v[230:231], off
	v_add_u32_e32 v229, 1, v229
	v_mad_u64_u32 v[230:231], s[2:3], v229, s50, v[14:15]
	global_load_dword v228, v[230:231], off
	v_add_u32_e32 v229, 1, v229
	v_mad_u64_u32 v[230:231], s[2:3], v229, s50, v[14:15]
	global_load_dword v228, v[230:231], off
	v_add_u32_e32 v229, 1, v229
	v_mad_u64_u32 v[230:231], s[2:3], v229, s50, v[14:15]
	global_load_dword v228, v[230:231], off
	v_add_u32_e32 v229, 1, v229
	v_mad_u64_u32 v[230:231], s[2:3], v229, s50, v[14:15]
	global_load_dword v228, v[230:231], off
	v_add_u32_e32 v229, 1, v229
	v_mad_u64_u32 v[230:231], s[2:3], v229, s50, v[14:15]
	global_load_dword v228, v[230:231], off
	v_add_u32_e32 v229, 1, v229
	v_mad_u64_u32 v[230:231], s[2:3], v229, s50, v[14:15]
	global_load_dword v228, v[230:231], off
	v_add_u32_e32 v229, 1, v229
	v_mad_u64_u32 v[230:231], s[2:3], v229, s50, v[14:15]
	global_load_dword v228, v[230:231], off
	v_add_u32_e32 v229, 1, v229
	v_mad_u64_u32 v[230:231], s[2:3], v229, s50, v[14:15]
	global_load_dword v228, v[230:231], off
	v_add_u32_e32 v229, 1, v229
	v_mad_u64_u32 v[230:231], s[2:3], v229, s50, v[14:15]
	global_load_dword v228, v[230:231], off
	v_add_u32_e32 v229, 1, v229
	v_mad_u64_u32 v[230:231], s[2:3], v229, s50, v[14:15]
	global_load_dword v228, v[230:231], off
	v_add_u32_e32 v229, 1, v229
	v_mad_u64_u32 v[230:231], s[2:3], v229, s50, v[14:15]
	global_load_dword v228, v[230:231], off
	v_add_u32_e32 v229, 1, v229
	v_mad_u64_u32 v[230:231], s[2:3], v229, s50, v[14:15]
	global_load_dword v228, v[230:231], off
	v_add_u32_e32 v229, 1, v229
	v_mad_u64_u32 v[230:231], s[2:3], v229, s50, v[14:15]
	global_load_dword v228, v[230:231], off
	v_add_u32_e32 v229, 1, v229
	v_mad_u64_u32 v[230:231], s[2:3], v229, s50, v[14:15]
	global_load_dword v228, v[230:231], off
	s_and_b64 s[2:3], vcc, s[0:1]
	v_mov_b32_e32 v0, 0
	s_and_saveexec_b64 s[0:1], s[2:3]
	s_cbranch_execz .LBB0_868
	v_mad_u64_u32 v[20:21], s[2:3], v17, s50, v[14:15]
	global_load_dword v0, v[20:21], off
